# cache policy: P5 read-once residual x loads also marked non-temporal; on top of v85
# speedup vs baseline: 1.0205x; 1.0014x over previous
;     __device__ __forceinline__ void operator()(f32x4 (&acc)[2][2][4][2], const Unit& u, int wr, int wc, int fr, int fq, LAS unsigned char* lds) const {
;     ...
;             const float* gr = gatef + (u.pm >> 3) * DM + col0;
;             f32x4 gv[2][2];
; #pragma unroll
;             for (int bj = 0; bj < 2; ++bj) { gv[bj][0] = *(const f32x4*)(gr + bj * HALF); gv[bj][1] = *(const f32x4*)(gr + bj * HALF + 4); }
; #pragma unroll
;             for (int ai = 0; ai < 2; ++ai)
; #pragma unroll
;                 for (int m = 0; m < 4; ++m) { int rr_ = row0 + ai * HALF + m * 16; asm volatile("" : "+v"(rr_)); const float* xr = xp + (size_t)rr_ * DM + col0;
;                     float sq = 0.f;
; #pragma unroll
;                     for (int bj = 0; bj < 2; ++bj) { const f32x4 v0 = *(const f32x4*)(xr + bj * HALF) + gv[bj][0] * acc[ai][bj][m][0], v1 = *(const f32x4*)(xr + bj * HALF + 4) + gv[bj][1] * acc[ai][bj][m][1];
;                         acc[ai][bj][m][0] = v0; acc[ai][bj][m][1] = v1;
;                         sq += ((v0[0] * v0[0] + v0[1] * v0[1]) + (v0[2] * v0[2] + v0[3] * v0[3])) + ((v1[0] * v1[0] + v1[1] * v1[1]) + (v1[2] * v1[2] + v1[3] * v1[3])); }
;                     sq += __shfl_xor(sq, 16); sq += __shfl_xor(sq, 32);
;                     if (fq == 0) P[(ai * HALF + wr * 64 + m * 16 + fr) * 4 + wc] = sq; }
.LBB0_1217:
	s_lshl_b32 s4, s73, 8
	s_add_i32 s16, s4, s62
	s_lshl_b32 s4, s73, 7
	s_and_b32 s4, s4, 0xfffffc00
	v_mov_b32_e32 v160, v180
	s_ashr_i32 s5, s4, 31
	s_lshl_b64 s[4:5], s[4:5], 2
	v_bfe_u32 v190, v160, 4, 2
	v_and_b32_e32 v159, 15, v160
	v_lshl_or_b32 v116, v190, 3, s68
	s_add_u32 s4, s22, s4
	v_or_b32_e32 v158, s16, v159
	s_addc_u32 s5, s23, s5
	v_lshlrev_b32_e32 v152, 2, v116
	v_mov_b32_e32 v162, v158
	global_load_dwordx4 v[128:131], v152, s[4:5] offset:16
	global_load_dwordx4 v[132:135], v152, s[4:5]
	global_load_dwordx4 v[116:119], v152, s[4:5] offset:528
	global_load_dwordx4 v[124:127], v152, s[4:5] offset:512
	v_xor_b32_e32 v161, 16, v176
	v_ashrrev_i32_e32 v163, 31, v162
	v_lshlrev_b64 v[162:163], 12, v[162:163]
	v_lshl_add_u64 v[162:163], s[36:37], 0, v[162:163]
	v_lshl_add_u64 v[174:175], v[162:163], 0, v[152:153]
	global_load_dwordx4 v[218:221], v[174:175], off nt
	global_load_dwordx4 v[222:225], v[174:175], off offset:16 nt
	global_load_dwordx4 v[226:229], v[174:175], off offset:512 nt
	global_load_dwordx4 v[230:233], v[174:175], off offset:528 nt
	v_add_u32_e32 v250, 16, v158
	v_ashrrev_i32_e32 v251, 31, v250
	v_lshlrev_b64 v[250:251], 12, v[250:251]
	v_lshl_add_u64 v[250:251], s[36:37], 0, v[250:251]
	v_lshl_add_u64 v[250:251], v[250:251], 0, v[152:153]
	global_load_dwordx4 v[234:237], v[250:251], off nt
	global_load_dwordx4 v[238:241], v[250:251], off offset:16 nt
	global_load_dwordx4 v[242:245], v[250:251], off offset:512 nt
	global_load_dwordx4 v[246:249], v[250:251], off offset:528 nt
	v_and_b32_e32 v174, 64, v176
	v_add_u32_e32 v179, 64, v174
	v_cmp_lt_i32_e32 vcc, v161, v179
	s_waitcnt vmcnt(4)
	v_pk_fma_f32 v[142:143], v[142:143], v[134:135], v[220:221]
	v_cndmask_b32_e32 v161, v176, v161, vcc
	v_pk_fma_f32 v[162:163], v[140:141], v[132:133], v[218:219]
	v_pk_fma_f32 v[138:139], v[138:139], v[130:131], v[224:225]
	v_pk_fma_f32 v[140:141], v[136:137], v[128:129], v[222:223]
	v_pk_fma_f32 v[122:123], v[122:123], v[126:127], v[228:229]
	v_pk_fma_f32 v[136:137], v[120:121], v[124:125], v[226:227]
	v_pk_fma_f32 v[114:115], v[114:115], v[118:119], v[232:233]
	v_pk_fma_f32 v[120:121], v[112:113], v[116:117], v[230:231]
	v_lshlrev_b32_e32 v177, 2, v161
	v_mul_f32_e32 v112, v163, v163
	v_mul_f32_e32 v113, v143, v143
	v_mul_f32_e32 v161, v141, v141
	v_mul_f32_e32 v164, v139, v139
	v_mul_f32_e32 v165, v137, v137
	v_mul_f32_e32 v166, v123, v123
	v_mul_f32_e32 v167, v121, v121
	v_mul_f32_e32 v168, v115, v115
	v_fmac_f32_e32 v112, v162, v162
	v_fmac_f32_e32 v113, v142, v142
	v_fmac_f32_e32 v161, v140, v140
	v_fmac_f32_e32 v164, v138, v138
	v_fmac_f32_e32 v165, v136, v136
	v_fmac_f32_e32 v166, v122, v122
	v_fmac_f32_e32 v167, v120, v120
	v_fmac_f32_e32 v168, v114, v114
	v_add_f32_e32 v112, v112, v113
	v_add_f32_e32 v113, v161, v164
	v_add_f32_e32 v161, v165, v166
	v_add_f32_e32 v164, v167, v168
	v_add_f32_e32 v112, v112, v113
	v_add_f32_e32 v113, v161, v164
	v_add_f32_e32 v112, v112, v113
	ds_bpermute_b32 v113, v177, v112
	v_xor_b32_e32 v161, 32, v176
	v_cmp_lt_i32_e32 vcc, v161, v179
	s_waitcnt lgkmcnt(0)
	v_add_f32_e32 v112, v112, v113
	v_cndmask_b32_e32 v161, v176, v161, vcc
	v_lshlrev_b32_e32 v178, 2, v161
	ds_bpermute_b32 v161, v178, v112
	v_or_b32_e32 v113, s62, v159
	v_cmp_eq_u32_e32 vcc, 0, v190
	v_lshl_add_u32 v113, v113, 4, s66
	s_and_saveexec_b64 s[4:5], vcc
	s_cbranch_execz .LBB0_1219
	s_waitcnt lgkmcnt(0)
	v_add_f32_e32 v112, v112, v161
	ds_write_b32 v113, v112
.LBB0_1219:
	s_or_b64 exec, exec, s[4:5]
	v_or_b32_e32 v112, 16, v158
	v_mov_b32_e32 v164, v112
	s_nop 0
	v_ashrrev_i32_e32 v165, 31, v164
	v_lshlrev_b64 v[164:165], 12, v[164:165]
	v_lshl_add_u64 v[164:165], s[36:37], 0, v[164:165]
	v_lshl_add_u64 v[186:187], v[164:165], 0, v[152:153]
	v_add_u32_e32 v250, 32, v158
	v_ashrrev_i32_e32 v251, 31, v250
	v_lshlrev_b64 v[250:251], 12, v[250:251]
	v_lshl_add_u64 v[250:251], s[36:37], 0, v[250:251]
	v_lshl_add_u64 v[250:251], v[250:251], 0, v[152:153]
	global_load_dwordx4 v[218:221], v[250:251], off nt
	global_load_dwordx4 v[222:225], v[250:251], off offset:16 nt
	global_load_dwordx4 v[226:229], v[250:251], off offset:512 nt
	global_load_dwordx4 v[230:233], v[250:251], off offset:528 nt
	s_nop 0
	s_waitcnt vmcnt(4)
	v_pk_fma_f32 v[110:111], v[110:111], v[134:135], v[236:237]
	v_pk_fma_f32 v[164:165], v[108:109], v[132:133], v[234:235]
	v_pk_fma_f32 v[106:107], v[106:107], v[130:131], v[240:241]
	v_pk_fma_f32 v[108:109], v[104:105], v[128:129], v[238:239]
	v_pk_fma_f32 v[102:103], v[102:103], v[126:127], v[244:245]
	v_pk_fma_f32 v[104:105], v[100:101], v[124:125], v[242:243]
	v_pk_fma_f32 v[98:99], v[98:99], v[118:119], v[248:249]
	v_pk_fma_f32 v[100:101], v[96:97], v[116:117], v[246:247]
	v_mul_f32_e32 v96, v165, v165
	v_mul_f32_e32 v97, v111, v111
	s_waitcnt lgkmcnt(0)
	v_mul_f32_e32 v161, v109, v109
	v_mul_f32_e32 v166, v107, v107
	v_mul_f32_e32 v167, v105, v105
	v_mul_f32_e32 v168, v103, v103
	v_mul_f32_e32 v169, v101, v101
	v_mul_f32_e32 v170, v99, v99
	v_fmac_f32_e32 v96, v164, v164
	v_fmac_f32_e32 v97, v110, v110
	v_fmac_f32_e32 v161, v108, v108
	v_fmac_f32_e32 v166, v106, v106
	v_fmac_f32_e32 v167, v104, v104
	v_fmac_f32_e32 v168, v102, v102
	v_fmac_f32_e32 v169, v100, v100
	v_fmac_f32_e32 v170, v98, v98
	v_add_f32_e32 v96, v96, v97
	v_add_f32_e32 v97, v161, v166
	v_add_f32_e32 v161, v167, v168
	v_add_f32_e32 v166, v169, v170
	v_add_f32_e32 v96, v96, v97
	v_add_f32_e32 v97, v161, v166
	v_add_f32_e32 v96, v96, v97
	ds_bpermute_b32 v97, v177, v96
	s_waitcnt lgkmcnt(0)
	v_add_f32_e32 v96, v96, v97
	ds_bpermute_b32 v97, v178, v96
	s_and_saveexec_b64 s[4:5], vcc
	s_cbranch_execz .LBB0_1221
	s_waitcnt lgkmcnt(0)
	v_add_f32_e32 v96, v96, v97
	ds_write_b32 v113, v96 offset:256
;     __device__ __forceinline__ void operator()(f32x4 (&acc)[2][2][4][2], const Unit& u, int wr, int wc, int fr, int fq, LAS unsigned char* lds) const {
;     ...
;                 for (int m = 0; m < 4; ++m) { int rr_ = row0 + ai * HALF + m * 16; asm volatile("" : "+v"(rr_)); const float* xr = xp + (size_t)rr_ * DM + col0;
;                     float sq = 0.f;
; #pragma unroll
;                     for (int bj = 0; bj < 2; ++bj) { const f32x4 v0 = *(const f32x4*)(xr + bj * HALF) + gv[bj][0] * acc[ai][bj][m][0], v1 = *(const f32x4*)(xr + bj * HALF + 4) + gv[bj][1] * acc[ai][bj][m][1];
;                         acc[ai][bj][m][0] = v0; acc[ai][bj][m][1] = v1;
;                         sq += ((v0[0] * v0[0] + v0[1] * v0[1]) + (v0[2] * v0[2] + v0[3] * v0[3])) + ((v1[0] * v1[0] + v1[1] * v1[1]) + (v1[2] * v1[2] + v1[3] * v1[3])); }
;                     sq += __shfl_xor(sq, 16); sq += __shfl_xor(sq, 32);
;                     if (fq == 0) P[(ai * HALF + wr * 64 + m * 16 + fr) * 4 + wc] = sq; }
.LBB0_1221:
	s_or_b64 exec, exec, s[4:5]
	v_or_b32_e32 v96, 32, v158
	v_mov_b32_e32 v166, v96
	s_nop 0
	v_ashrrev_i32_e32 v167, 31, v166
	v_lshlrev_b64 v[166:167], 12, v[166:167]
	v_lshl_add_u64 v[166:167], s[36:37], 0, v[166:167]
	v_lshl_add_u64 v[174:175], v[166:167], 0, v[152:153]
	v_add_u32_e32 v250, 48, v158
	v_ashrrev_i32_e32 v251, 31, v250
	v_lshlrev_b64 v[250:251], 12, v[250:251]
	v_lshl_add_u64 v[250:251], s[36:37], 0, v[250:251]
	v_lshl_add_u64 v[250:251], v[250:251], 0, v[152:153]
	global_load_dwordx4 v[234:237], v[250:251], off nt
	global_load_dwordx4 v[238:241], v[250:251], off offset:16 nt
	global_load_dwordx4 v[242:245], v[250:251], off offset:512 nt
	global_load_dwordx4 v[246:249], v[250:251], off offset:528 nt
	s_waitcnt vmcnt(4)
	v_pk_fma_f32 v[94:95], v[94:95], v[134:135], v[220:221]
	v_pk_fma_f32 v[166:167], v[92:93], v[132:133], v[218:219]
	v_pk_fma_f32 v[90:91], v[90:91], v[130:131], v[224:225]
	v_pk_fma_f32 v[92:93], v[88:89], v[128:129], v[222:223]
	v_pk_fma_f32 v[86:87], v[86:87], v[126:127], v[228:229]
	v_pk_fma_f32 v[88:89], v[84:85], v[124:125], v[226:227]
	v_pk_fma_f32 v[82:83], v[82:83], v[118:119], v[232:233]
	v_pk_fma_f32 v[84:85], v[80:81], v[116:117], v[230:231]
	v_mul_f32_e32 v80, v167, v167
	v_mul_f32_e32 v81, v95, v95
	s_waitcnt lgkmcnt(0)
	v_mul_f32_e32 v97, v93, v93
	v_mul_f32_e32 v161, v91, v91
	v_mul_f32_e32 v168, v89, v89
	v_mul_f32_e32 v169, v87, v87
	v_mul_f32_e32 v170, v85, v85
	v_mul_f32_e32 v171, v83, v83
	v_fmac_f32_e32 v80, v166, v166
	v_fmac_f32_e32 v81, v94, v94
	v_fmac_f32_e32 v97, v92, v92
	v_fmac_f32_e32 v161, v90, v90
	v_fmac_f32_e32 v168, v88, v88
	v_fmac_f32_e32 v169, v86, v86
	v_fmac_f32_e32 v170, v84, v84
	v_fmac_f32_e32 v171, v82, v82
	v_add_f32_e32 v80, v80, v81
	v_add_f32_e32 v81, v97, v161
	v_add_f32_e32 v97, v168, v169
	v_add_f32_e32 v161, v170, v171
	v_add_f32_e32 v80, v80, v81
	v_add_f32_e32 v81, v97, v161
	v_add_f32_e32 v80, v80, v81
	ds_bpermute_b32 v81, v177, v80
	s_waitcnt lgkmcnt(0)
	v_add_f32_e32 v80, v80, v81
	ds_bpermute_b32 v81, v178, v80
	s_and_saveexec_b64 s[4:5], vcc
	s_cbranch_execz .LBB0_1223
	s_waitcnt lgkmcnt(0)
	v_add_f32_e32 v80, v80, v81
	ds_write_b32 v113, v80 offset:512
.LBB0_1223:
	s_or_b64 exec, exec, s[4:5]
	v_or_b32_e32 v80, 48, v158
	v_mov_b32_e32 v168, v80
	s_nop 0
	v_ashrrev_i32_e32 v169, 31, v168
	v_lshlrev_b64 v[168:169], 12, v[168:169]
	v_lshl_add_u64 v[168:169], s[36:37], 0, v[168:169]
	v_lshl_add_u64 v[190:191], v[168:169], 0, v[152:153]
	v_add_u32_e32 v250, 128, v158
	v_ashrrev_i32_e32 v251, 31, v250
	v_lshlrev_b64 v[250:251], 12, v[250:251]
	v_lshl_add_u64 v[250:251], s[36:37], 0, v[250:251]
	v_lshl_add_u64 v[250:251], v[250:251], 0, v[152:153]
	global_load_dwordx4 v[218:221], v[250:251], off nt
	global_load_dwordx4 v[222:225], v[250:251], off offset:16 nt
	global_load_dwordx4 v[226:229], v[250:251], off offset:512 nt
	global_load_dwordx4 v[230:233], v[250:251], off offset:528 nt
	s_nop 0
	s_waitcnt vmcnt(4)
	v_pk_fma_f32 v[78:79], v[78:79], v[134:135], v[236:237]
	v_pk_fma_f32 v[76:77], v[76:77], v[132:133], v[234:235]
	v_pk_fma_f32 v[74:75], v[74:75], v[130:131], v[240:241]
	v_pk_fma_f32 v[72:73], v[72:73], v[128:129], v[238:239]
	v_pk_fma_f32 v[70:71], v[70:71], v[126:127], v[244:245]
	v_pk_fma_f32 v[68:69], v[68:69], v[124:125], v[242:243]
	v_pk_fma_f32 v[66:67], v[66:67], v[118:119], v[248:249]
	v_pk_fma_f32 v[64:65], v[64:65], v[116:117], v[246:247]
	s_waitcnt lgkmcnt(0)
	v_mul_f32_e32 v81, v77, v77
	v_mul_f32_e32 v97, v79, v79
	v_mul_f32_e32 v161, v73, v73
	v_mul_f32_e32 v168, v75, v75
	v_mul_f32_e32 v169, v69, v69
	v_mul_f32_e32 v170, v71, v71
	v_mul_f32_e32 v171, v65, v65
	v_mul_f32_e32 v172, v67, v67
	v_fmac_f32_e32 v81, v76, v76
	v_fmac_f32_e32 v97, v78, v78
	v_fmac_f32_e32 v161, v72, v72
	v_fmac_f32_e32 v168, v74, v74
	v_fmac_f32_e32 v169, v68, v68
	v_fmac_f32_e32 v170, v70, v70
	v_fmac_f32_e32 v171, v64, v64
	v_fmac_f32_e32 v172, v66, v66
	v_add_f32_e32 v81, v81, v97
	v_add_f32_e32 v97, v161, v168
	v_add_f32_e32 v161, v169, v170
	v_add_f32_e32 v168, v171, v172
	v_add_f32_e32 v81, v81, v97
	v_add_f32_e32 v97, v161, v168
	v_add_f32_e32 v81, v81, v97
	ds_bpermute_b32 v97, v177, v81
	s_waitcnt lgkmcnt(0)
	v_add_f32_e32 v81, v81, v97
	ds_bpermute_b32 v97, v178, v81
	s_and_saveexec_b64 s[4:5], vcc
	s_cbranch_execz .LBB0_1225
	s_waitcnt lgkmcnt(0)
	v_add_f32_e32 v81, v81, v97
	ds_write_b32 v113, v81 offset:768
.LBB0_1225:
	s_or_b64 exec, exec, s[4:5]
	v_add_u32_e32 v168, 0x80, v158
	v_mov_b32_e32 v170, v168
	s_nop 0
	v_ashrrev_i32_e32 v171, 31, v170
	v_lshlrev_b64 v[170:171], 12, v[170:171]
	v_lshl_add_u64 v[170:171], s[36:37], 0, v[170:171]
	v_lshl_add_u64 v[174:175], v[170:171], 0, v[152:153]
	v_add_u32_e32 v250, 144, v158
	v_ashrrev_i32_e32 v251, 31, v250
	v_lshlrev_b64 v[250:251], 12, v[250:251]
	v_lshl_add_u64 v[250:251], s[36:37], 0, v[250:251]
	v_lshl_add_u64 v[250:251], v[250:251], 0, v[152:153]
	global_load_dwordx4 v[234:237], v[250:251], off nt
	global_load_dwordx4 v[238:241], v[250:251], off offset:16 nt
	global_load_dwordx4 v[242:245], v[250:251], off offset:512 nt
	global_load_dwordx4 v[246:249], v[250:251], off offset:528 nt
	s_waitcnt vmcnt(4)
	v_pk_fma_f32 v[62:63], v[62:63], v[134:135], v[220:221]
	v_pk_fma_f32 v[60:61], v[60:61], v[132:133], v[218:219]
	v_pk_fma_f32 v[58:59], v[58:59], v[130:131], v[224:225]
	v_pk_fma_f32 v[56:57], v[56:57], v[128:129], v[222:223]
	v_pk_fma_f32 v[54:55], v[54:55], v[126:127], v[228:229]
	v_pk_fma_f32 v[52:53], v[52:53], v[124:125], v[226:227]
	v_pk_fma_f32 v[50:51], v[50:51], v[118:119], v[232:233]
	v_pk_fma_f32 v[48:49], v[48:49], v[116:117], v[230:231]
	v_mul_f32_e32 v81, v61, v61
	s_waitcnt lgkmcnt(0)
	v_mul_f32_e32 v97, v63, v63
	v_mul_f32_e32 v161, v57, v57
	v_mul_f32_e32 v169, v59, v59
	v_mul_f32_e32 v170, v53, v53
	v_mul_f32_e32 v171, v55, v55
	v_mul_f32_e32 v172, v49, v49
	v_mul_f32_e32 v173, v51, v51
	v_fmac_f32_e32 v81, v60, v60
	v_fmac_f32_e32 v97, v62, v62
	v_fmac_f32_e32 v161, v56, v56
	v_fmac_f32_e32 v169, v58, v58
	v_fmac_f32_e32 v170, v52, v52
	v_fmac_f32_e32 v171, v54, v54
	v_fmac_f32_e32 v172, v48, v48
	v_fmac_f32_e32 v173, v50, v50
	v_add_f32_e32 v81, v81, v97
	v_add_f32_e32 v97, v161, v169
	v_add_f32_e32 v161, v170, v171
	v_add_f32_e32 v169, v172, v173
	v_add_f32_e32 v81, v81, v97
	v_add_f32_e32 v97, v161, v169
	v_add_f32_e32 v81, v81, v97
	ds_bpermute_b32 v97, v177, v81
	s_waitcnt lgkmcnt(0)
	v_add_f32_e32 v81, v81, v97
	ds_bpermute_b32 v97, v178, v81
	s_and_saveexec_b64 s[4:5], vcc
	s_cbranch_execz .LBB0_1227
	s_waitcnt lgkmcnt(0)
	v_add_f32_e32 v81, v81, v97
	ds_write_b32 v113, v81 offset:2048
;     __device__ __forceinline__ void operator()(f32x4 (&acc)[2][2][4][2], const Unit& u, int wr, int wc, int fr, int fq, LAS unsigned char* lds) const {
;     ...
;                 for (int m = 0; m < 4; ++m) { int rr_ = row0 + ai * HALF + m * 16; asm volatile("" : "+v"(rr_)); const float* xr = xp + (size_t)rr_ * DM + col0;
;                     float sq = 0.f;
; #pragma unroll
;                     for (int bj = 0; bj < 2; ++bj) { const f32x4 v0 = *(const f32x4*)(xr + bj * HALF) + gv[bj][0] * acc[ai][bj][m][0], v1 = *(const f32x4*)(xr + bj * HALF + 4) + gv[bj][1] * acc[ai][bj][m][1];
;                         acc[ai][bj][m][0] = v0; acc[ai][bj][m][1] = v1;
;                         sq += ((v0[0] * v0[0] + v0[1] * v0[1]) + (v0[2] * v0[2] + v0[3] * v0[3])) + ((v1[0] * v1[0] + v1[1] * v1[1]) + (v1[2] * v1[2] + v1[3] * v1[3])); }
;                     sq += __shfl_xor(sq, 16); sq += __shfl_xor(sq, 32);
;                     if (fq == 0) P[(ai * HALF + wr * 64 + m * 16 + fr) * 4 + wc] = sq; }
.LBB0_1227:
	s_or_b64 exec, exec, s[4:5]
	v_add_u32_e32 v170, 0x90, v158
	v_mov_b32_e32 v172, v170
	s_nop 0
	v_ashrrev_i32_e32 v173, 31, v172
	v_lshlrev_b64 v[172:173], 12, v[172:173]
	v_lshl_add_u64 v[172:173], s[36:37], 0, v[172:173]
	v_lshl_add_u64 v[194:195], v[172:173], 0, v[152:153]
	v_add_u32_e32 v250, 160, v158
	v_ashrrev_i32_e32 v251, 31, v250
	v_lshlrev_b64 v[250:251], 12, v[250:251]
	v_lshl_add_u64 v[250:251], s[36:37], 0, v[250:251]
	v_lshl_add_u64 v[250:251], v[250:251], 0, v[152:153]
	global_load_dwordx4 v[218:221], v[250:251], off nt
	global_load_dwordx4 v[222:225], v[250:251], off offset:16 nt
	global_load_dwordx4 v[226:229], v[250:251], off offset:512 nt
	global_load_dwordx4 v[230:233], v[250:251], off offset:528 nt
	s_nop 0
	s_waitcnt vmcnt(4)
	v_pk_fma_f32 v[46:47], v[46:47], v[134:135], v[236:237]
	v_pk_fma_f32 v[44:45], v[44:45], v[132:133], v[234:235]
	v_pk_fma_f32 v[42:43], v[42:43], v[130:131], v[240:241]
	v_pk_fma_f32 v[40:41], v[40:41], v[128:129], v[238:239]
	v_pk_fma_f32 v[38:39], v[38:39], v[126:127], v[244:245]
	v_pk_fma_f32 v[36:37], v[36:37], v[124:125], v[242:243]
	v_pk_fma_f32 v[34:35], v[34:35], v[118:119], v[248:249]
	v_pk_fma_f32 v[32:33], v[32:33], v[116:117], v[246:247]
	v_mul_f32_e32 v81, v45, v45
	s_waitcnt lgkmcnt(0)
	v_mul_f32_e32 v97, v47, v47
	v_mul_f32_e32 v161, v41, v41
	v_mul_f32_e32 v169, v43, v43
	v_mul_f32_e32 v171, v37, v37
	v_mul_f32_e32 v172, v39, v39
	v_mul_f32_e32 v173, v33, v33
	v_mul_f32_e32 v174, v35, v35
	v_fmac_f32_e32 v81, v44, v44
	v_fmac_f32_e32 v97, v46, v46
	v_fmac_f32_e32 v161, v40, v40
	v_fmac_f32_e32 v169, v42, v42
	v_fmac_f32_e32 v171, v36, v36
	v_fmac_f32_e32 v172, v38, v38
	v_fmac_f32_e32 v173, v32, v32
	v_fmac_f32_e32 v174, v34, v34
	v_add_f32_e32 v81, v81, v97
	v_add_f32_e32 v97, v161, v169
	v_add_f32_e32 v161, v171, v172
	v_add_f32_e32 v169, v173, v174
	v_add_f32_e32 v81, v81, v97
	v_add_f32_e32 v97, v161, v169
	v_add_f32_e32 v81, v81, v97
	ds_bpermute_b32 v97, v177, v81
	s_waitcnt lgkmcnt(0)
	v_add_f32_e32 v81, v81, v97
	ds_bpermute_b32 v97, v178, v81
	s_and_saveexec_b64 s[4:5], vcc
	s_cbranch_execz .LBB0_1229
	s_waitcnt lgkmcnt(0)
	v_add_f32_e32 v81, v81, v97
	ds_write_b32 v113, v81 offset:2304
.LBB0_1229:
	s_or_b64 exec, exec, s[4:5]
	v_add_u32_e32 v172, 0xa0, v158
	v_mov_b32_e32 v174, v172
	s_nop 0
	v_ashrrev_i32_e32 v175, 31, v174
	v_lshlrev_b64 v[174:175], 12, v[174:175]
	v_lshl_add_u64 v[174:175], s[36:37], 0, v[174:175]
	v_lshl_add_u64 v[174:175], v[174:175], 0, v[152:153]
	v_add_u32_e32 v250, 176, v158
	v_ashrrev_i32_e32 v251, 31, v250
	v_lshlrev_b64 v[250:251], 12, v[250:251]
	v_lshl_add_u64 v[250:251], s[36:37], 0, v[250:251]
	v_lshl_add_u64 v[250:251], v[250:251], 0, v[152:153]
	global_load_dwordx4 v[234:237], v[250:251], off nt
	global_load_dwordx4 v[238:241], v[250:251], off offset:16 nt
	global_load_dwordx4 v[242:245], v[250:251], off offset:512 nt
	global_load_dwordx4 v[246:249], v[250:251], off offset:528 nt
	s_waitcnt vmcnt(4)
	v_pk_fma_f32 v[30:31], v[30:31], v[134:135], v[220:221]
	v_pk_fma_f32 v[28:29], v[28:29], v[132:133], v[218:219]
	v_pk_fma_f32 v[26:27], v[26:27], v[130:131], v[224:225]
	v_pk_fma_f32 v[24:25], v[24:25], v[128:129], v[222:223]
	v_pk_fma_f32 v[22:23], v[22:23], v[126:127], v[228:229]
	v_pk_fma_f32 v[20:21], v[20:21], v[124:125], v[226:227]
	v_pk_fma_f32 v[18:19], v[18:19], v[118:119], v[232:233]
	v_pk_fma_f32 v[16:17], v[16:17], v[116:117], v[230:231]
	v_mul_f32_e32 v81, v29, v29
	s_waitcnt lgkmcnt(0)
	v_mul_f32_e32 v97, v31, v31
	v_mul_f32_e32 v161, v25, v25
	v_mul_f32_e32 v169, v27, v27
	v_mul_f32_e32 v171, v21, v21
	v_mul_f32_e32 v173, v23, v23
	v_mul_f32_e32 v174, v17, v17
	v_mul_f32_e32 v175, v19, v19
	v_fmac_f32_e32 v81, v28, v28
	v_fmac_f32_e32 v97, v30, v30
	v_fmac_f32_e32 v161, v24, v24
	v_fmac_f32_e32 v169, v26, v26
	v_fmac_f32_e32 v171, v20, v20
	v_fmac_f32_e32 v173, v22, v22
	v_fmac_f32_e32 v174, v16, v16
	v_fmac_f32_e32 v175, v18, v18
	v_add_f32_e32 v81, v81, v97
	v_add_f32_e32 v97, v161, v169
	v_add_f32_e32 v161, v171, v173
	v_add_f32_e32 v169, v174, v175
	v_add_f32_e32 v81, v81, v97
	v_add_f32_e32 v97, v161, v169
	v_add_f32_e32 v81, v81, v97
	ds_bpermute_b32 v97, v177, v81
	s_waitcnt lgkmcnt(0)
	v_add_f32_e32 v81, v81, v97
	ds_bpermute_b32 v97, v178, v81
	s_and_saveexec_b64 s[4:5], vcc
	s_cbranch_execz .LBB0_1231
	s_waitcnt lgkmcnt(0)
	v_add_f32_e32 v81, v81, v97
	ds_write_b32 v113, v81 offset:2560
